# S1 phase: GEMM workgroups hand 2 of their 4 conv tiles to workgroups 128..223 (on top of the p0a section reorder)
# baseline (speedup 1.0000x reference)
.LBB7_803:
	s_or_b64 exec, exec, s[6:7]
	v_readlane_b32 s4, v252, 7
	v_readlane_b32 s5, v252, 8
	s_andn2_b64 vcc, exec, s[4:5]
	s_cbranch_vccnz .LBB7_813
	s_load_dwordx8 s[12:19], s[42:43], 0xa0
	v_readlane_b32 s4, v250, 10
	v_readlane_b32 s5, v250, 11
	s_lshl_b64 s[4:5], s[4:5], 2
	v_readlane_b32 s3, v250, 27
	s_waitcnt lgkmcnt(0)
	s_add_u32 s6, s18, s4
	s_addc_u32 s7, s19, s5
	s_add_u32 s8, s16, s4
	s_addc_u32 s9, s17, s5
	s_add_u32 s12, s12, s3
	s_movk_i32 s3, 0xba0
	s_addc_u32 s13, s13, 0
	v_cmp_gt_i32_e32 vcc, s3, v150
	s_movk_i32 s3, 0x180
	s_add_u32 s4, s14, s4
	v_cmp_gt_i32_e64 s[40:41], s3, v150
	v_ashrrev_i32_e32 v151, 31, v150
	v_lshlrev_b32_e32 v0, 2, v150
	v_readlane_b32 s3, v253, 39
	s_addc_u32 s5, s15, s5
	v_lshlrev_b64 v[2:3], 2, v[150:151]
	v_add_u32_e32 v108, 0, v0
	v_add_u32_e32 v109, s3, v0
	v_mov_b32_e32 v0, s3
	v_lshl_add_u64 v[10:11], s[4:5], 0, v[2:3]
	v_mad_u64_u32 v[12:13], s[4:5], v204, 24, v[0:1]
	v_lshl_add_u64 v[14:15], s[12:13], 0, v[2:3]
	s_mov_b64 s[4:5], 0x1200
	v_lshl_add_u64 v[16:17], v[14:15], 0, s[4:5]
	s_mov_b64 s[4:5], 0x1800
	v_lshl_add_u64 v[18:19], v[14:15], 0, s[4:5]
	s_mov_b64 s[4:5], 0x1e00
	v_lshl_add_u64 v[20:21], v[14:15], 0, s[4:5]
	s_mov_b64 s[4:5], 0x2400
	v_lshl_add_u64 v[22:23], v[14:15], 0, s[4:5]
	s_mov_b64 s[4:5], 0x2a00
	v_lshl_add_u64 v[24:25], v[14:15], 0, s[4:5]
	s_mov_b64 s[4:5], 0x3000
	v_lshl_add_u64 v[26:27], v[14:15], 0, s[4:5]
	s_mov_b64 s[4:5], 0x3600
	v_and_b32_e32 v0, 64, v163
	v_lshl_add_u64 v[28:29], v[14:15], 0, s[4:5]
	s_mov_b64 s[4:5], 0x3c00
	v_add_u32_e32 v0, 64, v0
	v_xor_b32_e32 v4, 1, v163
	v_lshl_add_u64 v[30:31], v[14:15], 0, s[4:5]
	s_mov_b64 s[4:5], 0x4200
	v_cmp_lt_i32_e64 s[42:43], v4, v0
	v_lshl_add_u64 v[32:33], v[14:15], 0, s[4:5]
	s_mov_b64 s[4:5], 0x4800
	v_cndmask_b32_e64 v4, v163, v4, s[42:43]
	v_lshl_add_u64 v[34:35], v[14:15], 0, s[4:5]
	s_mov_b64 s[4:5], 0x4e00
	v_lshlrev_b32_e32 v13, 2, v4
	v_xor_b32_e32 v4, 2, v163
	v_lshl_add_u64 v[36:37], v[14:15], 0, s[4:5]
	s_mov_b64 s[4:5], 0x5400
	v_cmp_lt_i32_e64 s[42:43], v4, v0
	v_lshl_add_u64 v[38:39], v[14:15], 0, s[4:5]
	s_mov_b64 s[4:5], 0x5a00
	v_cndmask_b32_e64 v4, v163, v4, s[42:43]
	v_lshl_add_u64 v[40:41], v[14:15], 0, s[4:5]
	s_mov_b64 s[4:5], 0x6000
	v_lshlrev_b32_e32 v110, 2, v4
	v_xor_b32_e32 v4, 4, v163
	v_lshl_add_u64 v[42:43], v[14:15], 0, s[4:5]
	s_mov_b64 s[4:5], 0x6600
	v_cmp_lt_i32_e64 s[42:43], v4, v0
	v_lshl_add_u64 v[44:45], v[14:15], 0, s[4:5]
	s_mov_b64 s[4:5], 0x6c00
	v_cndmask_b32_e64 v4, v163, v4, s[42:43]
	v_lshl_add_u64 v[46:47], v[14:15], 0, s[4:5]
	s_mov_b64 s[4:5], 0x7200
	v_lshlrev_b32_e32 v111, 2, v4
	v_xor_b32_e32 v4, 8, v163
	v_lshl_add_u64 v[48:49], v[14:15], 0, s[4:5]
	s_mov_b64 s[4:5], 0x7800
	v_cmp_lt_i32_e64 s[42:43], v4, v0
	v_lshl_add_u64 v[50:51], v[14:15], 0, s[4:5]
	s_mov_b64 s[4:5], 0x7e00
	v_cndmask_b32_e64 v4, v163, v4, s[42:43]
	v_lshl_add_u64 v[52:53], v[14:15], 0, s[4:5]
	s_mov_b64 s[4:5], 0x8400
	v_lshlrev_b32_e32 v112, 2, v4
	v_xor_b32_e32 v4, 16, v163
	v_lshl_add_u64 v[54:55], v[14:15], 0, s[4:5]
	s_mov_b64 s[4:5], 0x8a00
	v_cmp_lt_i32_e64 s[42:43], v4, v0
	v_lshl_add_u64 v[56:57], v[14:15], 0, s[4:5]
	s_mov_b64 s[4:5], 0x9000
	v_cndmask_b32_e64 v4, v163, v4, s[42:43]
	v_lshl_add_u64 v[58:59], v[14:15], 0, s[4:5]
	s_mov_b64 s[4:5], 0x9600
	v_lshlrev_b32_e32 v113, 2, v4
	v_xor_b32_e32 v4, 32, v163
	v_lshl_add_u64 v[60:61], v[14:15], 0, s[4:5]
	s_mov_b64 s[4:5], 0x9c00
	v_cmp_lt_i32_e64 s[42:43], v4, v0
	v_lshl_add_u64 v[62:63], v[14:15], 0, s[4:5]
	s_mov_b64 s[4:5], 0xa200
	v_cndmask_b32_e64 v0, v163, v4, s[42:43]
	v_mul_lo_u32 v4, v204, 6
	v_lshl_add_u64 v[64:65], v[14:15], 0, s[4:5]
	s_mov_b64 s[4:5], 0xa800
	v_ashrrev_i32_e32 v5, 31, v4
	v_lshl_add_u64 v[66:67], v[14:15], 0, s[4:5]
	s_mov_b64 s[4:5], 0xae00
	v_lshl_add_u64 v[68:69], v[14:15], 0, s[4:5]
	s_mov_b64 s[4:5], 0xb400
	v_lshlrev_b64 v[2:3], 2, v[4:5]
	v_lshlrev_b32_e32 v114, 2, v0
	v_lshl_add_u64 v[70:71], v[14:15], 0, s[4:5]
	v_add_u32_e32 v115, 0x10200, v108
	v_add_u32_e32 v116, 0x10800, v108
	v_add_u32_e32 v117, 0x10e00, v108
	v_add_u32_e32 v118, 0x11400, v108
	v_add_u32_e32 v119, 0x11a00, v108
	v_add_u32_e32 v120, 0x12000, v108
	v_add_u32_e32 v121, 0x12600, v108
	v_add_u32_e32 v122, 0x12c00, v108
	v_add_u32_e32 v123, 0x13200, v108
	v_add_u32_e32 v124, 0x13800, v108
	v_add_u32_e32 v125, 0x13e00, v108
	v_add_u32_e32 v126, 0x14400, v108
	v_add_u32_e32 v127, 0x14a00, v108
	v_add_u32_e32 v128, 0x15000, v108
	v_add_u32_e32 v129, 0x15600, v108
	v_add_u32_e32 v130, 0x15c00, v108
	v_add_u32_e32 v131, 0x16200, v108
	v_add_u32_e32 v132, 0x16800, v108
	v_add_u32_e32 v133, 0x16e00, v108
	v_lshl_add_u64 v[72:73], s[8:9], 0, v[2:3]
	v_lshl_add_u64 v[74:75], s[6:7], 0, v[2:3]
	v_lshl_add_u64 v[76:77], v[4:5], 1, s[0:1]
	s_and_saveexec_b64 s[4:5], s[40:41]
	global_load_dword v247, v[10:11], off
	global_load_dword v216, v[14:15], off
	global_load_dword v217, v[14:15], off offset:1536
	global_load_dword v218, v[14:15], off offset:3072
	global_load_dword v219, v[16:17], off
	global_load_dword v220, v[18:19], off
	global_load_dword v221, v[20:21], off
	global_load_dword v222, v[22:23], off
	global_load_dword v223, v[24:25], off
	global_load_dword v224, v[26:27], off
	global_load_dword v225, v[28:29], off
	global_load_dword v226, v[30:31], off
	global_load_dword v227, v[32:33], off
	global_load_dword v228, v[34:35], off
	global_load_dword v229, v[36:37], off
	global_load_dword v230, v[38:39], off
	global_load_dword v231, v[40:41], off
	global_load_dword v232, v[42:43], off
	global_load_dword v233, v[44:45], off
	global_load_dword v234, v[46:47], off
	global_load_dword v235, v[48:49], off
	global_load_dword v236, v[50:51], off
	global_load_dword v237, v[52:53], off
	global_load_dword v238, v[54:55], off
	global_load_dword v239, v[56:57], off
	global_load_dword v240, v[58:59], off
	global_load_dword v241, v[60:61], off
	global_load_dword v242, v[62:63], off
	global_load_dword v243, v[64:65], off
	global_load_dword v244, v[66:67], off
	global_load_dword v245, v[68:69], off
	global_load_dword v246, v[70:71], off
	s_or_b64 exec, exec, s[4:5]
	global_load_dwordx4 v[14:17], v[72:73], off
	global_load_dwordx2 v[18:19], v[72:73], off offset:16
	global_load_dwordx4 v[20:23], v[74:75], off
	global_load_dwordx2 v[10:11], v[74:75], off offset:16
	s_mov_b32 s12, s2
	s_movk_i32 s100, 0x400
	s_movk_i32 s101, 0x4000
	s_cmpk_eq_u32 s60, 0x100
	s_cbranch_scc0 .Lct_plain
	s_cmp_lt_u32 s2, 48
	s_cselect_b32 s100, 0x200, s100
	s_sub_u32 s15, s2, 0x80
	s_cmp_lt_u32 s15, 96
	s_cbranch_scc0 .Lct_plain
	s_add_u32 s101, s15, 0x200
	s_cmp_lt_u32 s15, 48
	s_cbranch_scc1 .Lct_plain
	s_add_u32 s101, s15, 0x2d0
